# NSA window/pass-2/pass-1 loops: step-end LDS staging waits only for the tile loaded one step earlier, K/V fragment reads batched ahead of the MFMAs (as in the selected loop), on top of gMLP LN-stat sh
# speedup vs baseline: 1.0612x; 1.0022x over previous
.LBB0_708:
	s_add_i32 s14, s2, 2
	s_cmp_lt_u32 s14, s12
	s_cselect_b64 s[10:11], -1, 0
	s_cmp_ge_u32 s14, s12
	s_cselect_b64 s[6:7], -1, 0
	s_and_b64 vcc, exec, s[6:7]
	s_cbranch_vccnz .LBB0_710
	v_add_co_u32_e32 v12, vcc, 0x2000, v50
	s_nop 1
	v_addc_co_u32_e32 v13, vcc, 0, v51, vcc
	global_load_dwordx4 v[12:15], v[12:13], off
.LBB0_710:
	v_cmp_ge_i32_e64 s[8:9], s13, v76
	s_mov_b64 s[4:5], -1
	s_and_b64 vcc, exec, s[8:9]
	v_add_u32_e32 v77, v58, v56
	s_cbranch_vccz .LBB0_732
	ds_read_b128 v[160:163], v77
	ds_read_b128 v[164:167], v77 offset:64
	ds_read_b128 v[168:171], v77 offset:2304
	ds_read_b128 v[172:175], v77 offset:2368
	ds_read_b128 v[176:179], v77 offset:4608
	ds_read_b128 v[180:183], v77 offset:4672
	ds_read_b128 v[184:187], v77 offset:6912
	ds_read_b128 v[188:191], v77 offset:6976
	v_cvt_f32_i32_e32 v20, v75
	s_mov_b32 s4, 2.0
	s_mov_b32 s5, 0x40400000
	v_mul_f32_e64 v32, -v96, v20
	v_fma_f32 v21, -v96, v20, v60
	v_mov_b32_e32 v20, v32
	v_fmac_f32_e32 v20, 0, v60
	v_pk_fma_f32 v[22:23], v[60:61], s[4:5], v[32:33] op_sel_hi:[1,1,0]
	s_mov_b32 s4, 0x41800000
	s_mov_b32 s5, 0x41880000
	s_waitcnt lgkmcnt(7)
	v_mfma_f32_16x16x32_bf16 v[20:23], v[160:163], v[4:7], v[20:23]
	v_pk_fma_f32 v[26:27], v[70:71], s[90:91], v[32:33] op_sel_hi:[1,1,0]
	v_pk_fma_f32 v[24:25], v[68:69], s[4:5], v[32:33] op_sel_hi:[1,1,0]
	v_pk_fma_f32 v[30:31], v[70:71], s[92:93], v[32:33] op_sel_hi:[1,1,0]
	v_pk_fma_f32 v[28:29], v[68:69], s[34:35], v[32:33] op_sel_hi:[1,1,0]
	s_waitcnt lgkmcnt(6)
	v_mfma_f32_16x16x32_bf16 v[20:23], v[164:167], v[8:11], v[20:23]
	v_pk_fma_f32 v[34:35], v[70:71], s[22:23], v[32:33] op_sel_hi:[1,1,0]
	v_pk_fma_f32 v[32:33], v[68:69], s[72:73], v[32:33] op_sel_hi:[1,1,0]
	s_nop 4
	s_nop 0
	v_max3_f32 v78, v20, s36, v21
	s_waitcnt lgkmcnt(5)
	v_mfma_f32_16x16x32_bf16 v[24:27], v[168:171], v[4:7], v[24:27]
	v_max3_f32 v78, v78, v22, v23
	s_waitcnt lgkmcnt(4)
	v_mfma_f32_16x16x32_bf16 v[24:27], v[172:175], v[8:11], v[24:27]
	s_nop 6
	s_nop 0
	v_max3_f32 v78, v78, v24, v25
	s_waitcnt lgkmcnt(3)
	v_mfma_f32_16x16x32_bf16 v[28:31], v[176:179], v[4:7], v[28:31]
	v_max3_f32 v78, v78, v26, v27
	s_waitcnt lgkmcnt(2)
	v_mfma_f32_16x16x32_bf16 v[28:31], v[180:183], v[8:11], v[28:31]
	s_nop 6
	s_nop 0
	v_max3_f32 v78, v78, v28, v29
	s_waitcnt lgkmcnt(1)
	v_mfma_f32_16x16x32_bf16 v[32:35], v[184:187], v[4:7], v[32:35]
	v_max3_f32 v78, v78, v30, v31
	s_waitcnt lgkmcnt(0)
	v_mfma_f32_16x16x32_bf16 v[32:35], v[188:191], v[8:11], v[32:35]
	s_nop 7
	v_max3_f32 v78, v78, v32, v33
	v_max3_f32 v78, v78, v34, v35
	s_cbranch_execz .LBB0_733

.LBB0_718:
	s_add_i32 s8, s2, 1
	s_cmp_lt_u32 s8, s12
	s_cselect_b64 s[4:5], -1, 0
	s_cmp_ge_u32 s8, s12
	s_cbranch_scc1 .LBB0_720
	s_and_b64 vcc, exec, s[10:11]
	s_cbranch_vccz .Lp1_e_old
	s_waitcnt vmcnt(1)
	ds_write_b128 v113, v[16:19]
	s_branch .LBB0_720
.Lp1_e_old:
	s_waitcnt vmcnt(0)
	ds_write_b128 v113, v[16:19]

.LBB0_723:
	s_xor_b32 s2, s2, -2
	s_add_i32 s2, s2, s12
	s_lshl_b32 s15, s2, 10
	s_or_b32 s8, s15, 0x3f0
	s_cmp_ge_i32 s13, s8
	s_cselect_b64 s[8:9], -1, 0
	s_mov_b64 s[4:5], -1
	s_and_b64 vcc, exec, s[8:9]
	v_add_u32_e32 v77, v57, v56
	s_cbranch_vccz .LBB0_734
	ds_read_b128 v[160:163], v77
	ds_read_b128 v[164:167], v77 offset:64
	ds_read_b128 v[168:171], v77 offset:2304
	ds_read_b128 v[172:175], v77 offset:2368
	ds_read_b128 v[176:179], v77 offset:4608
	ds_read_b128 v[180:183], v77 offset:4672
	ds_read_b128 v[184:187], v77 offset:6912
	ds_read_b128 v[188:191], v77 offset:6976
	v_subrev_u32_e32 v20, s15, v72
	v_cvt_f32_i32_e32 v20, v20
	s_mov_b32 s4, 2.0
	s_mov_b32 s5, 0x40400000
	v_mul_f32_e64 v32, -v96, v20
	v_fma_f32 v21, -v96, v20, v60
	v_mov_b32_e32 v20, v32
	v_fmac_f32_e32 v20, 0, v60
	v_pk_fma_f32 v[22:23], v[60:61], s[4:5], v[32:33] op_sel_hi:[1,1,0]
	s_mov_b32 s4, 0x41800000
	s_mov_b32 s5, 0x41880000
	s_waitcnt lgkmcnt(7)
	v_mfma_f32_16x16x32_bf16 v[20:23], v[160:163], v[4:7], v[20:23]
	v_pk_fma_f32 v[26:27], v[70:71], s[90:91], v[32:33] op_sel_hi:[1,1,0]
	v_pk_fma_f32 v[24:25], v[68:69], s[4:5], v[32:33] op_sel_hi:[1,1,0]
	v_pk_fma_f32 v[30:31], v[70:71], s[92:93], v[32:33] op_sel_hi:[1,1,0]
	s_waitcnt lgkmcnt(6)
	v_mfma_f32_16x16x32_bf16 v[20:23], v[164:167], v[8:11], v[20:23]
	v_pk_fma_f32 v[28:29], v[68:69], s[34:35], v[32:33] op_sel_hi:[1,1,0]
	v_pk_fma_f32 v[34:35], v[70:71], s[22:23], v[32:33] op_sel_hi:[1,1,0]
	s_waitcnt lgkmcnt(5)
	v_mfma_f32_16x16x32_bf16 v[24:27], v[168:171], v[4:7], v[24:27]
	v_pk_fma_f32 v[32:33], v[68:69], s[72:73], v[32:33] op_sel_hi:[1,1,0]
	s_nop 0
	s_nop 1
	v_max3_f32 v78, v20, s36, v21
	s_waitcnt lgkmcnt(4)
	v_mfma_f32_16x16x32_bf16 v[24:27], v[172:175], v[8:11], v[24:27]
	v_max3_f32 v78, v78, v22, v23
	s_waitcnt lgkmcnt(3)
	v_mfma_f32_16x16x32_bf16 v[28:31], v[176:179], v[4:7], v[28:31]
	s_nop 2
	s_nop 1
	v_max3_f32 v78, v78, v24, v25
	s_nop 0
	v_max3_f32 v78, v78, v26, v27
	s_waitcnt lgkmcnt(2)
	v_mfma_f32_16x16x32_bf16 v[28:31], v[180:183], v[8:11], v[28:31]
	s_nop 6
	s_nop 0
	v_max3_f32 v78, v78, v28, v29
	s_waitcnt lgkmcnt(1)
	v_mfma_f32_16x16x32_bf16 v[32:35], v[184:187], v[4:7], v[32:35]
	v_max3_f32 v78, v78, v30, v31
	s_waitcnt lgkmcnt(0)
	v_mfma_f32_16x16x32_bf16 v[32:35], v[188:191], v[8:11], v[32:35]
	s_nop 7
	v_max3_f32 v78, v78, v32, v33
	v_max3_f32 v78, v78, v34, v35
	s_cbranch_execz .LBB0_735

.LBB0_730:
	s_add_i32 s4, s14, 1
	s_cmp_lt_u32 s4, s12
	s_cbranch_scc0 .Lp1_o_old
	s_waitcnt vmcnt(1)
	ds_write_b128 v112, v[12:15]
	s_branch .LBB0_731

.LBB0_743:
	s_add_i32 s20, s15, -1
	s_cmp_lt_u32 s20, s12
	s_cselect_b64 s[0:1], -1, 0
	s_cmp_ge_u32 s20, s12
	s_cbranch_scc1 .LBB0_745
	v_add_co_u32_e32 v28, vcc, 0xffffe000, v76
	s_add_i32 s88, s17, 0x80
	s_nop 0
	v_addc_co_u32_e32 v29, vcc, -1, v77, vcc
	v_lshl_add_u64 v[32:33], s[88:89], 1, v[72:73]
	global_load_dwordx4 v[28:31], v[28:29], off offset:-8
	s_nop 0
	global_load_dwordx4 v[32:35], v[32:33], off

.LBB0_747:
	ds_read_b128 v[160:163], v118
	ds_read_b128 v[164:167], v118 offset:64
	ds_read_b128 v[168:171], v118 offset:2304
	ds_read_b128 v[172:175], v118 offset:2368
	ds_read_b128 v[176:179], v118 offset:4608
	ds_read_b128 v[180:183], v118 offset:4672
	ds_read_b128 v[184:187], v118 offset:6912
	ds_read_b128 v[188:191], v118 offset:6976
	v_cndmask_b32_e64 v78, 0, 1, s[4:5]
	s_mov_b64 s[6:7], -1
	v_cmp_ne_u32_e64 s[10:11], 1, v78
	s_andn2_b64 vcc, exec, s[4:5]
	s_waitcnt lgkmcnt(7)
	v_mfma_f32_16x16x32_bf16 v[52:55], v[160:163], v[4:7], v[52:55]
	s_waitcnt lgkmcnt(6)
	v_mfma_f32_16x16x32_bf16 v[52:55], v[164:167], v[8:11], v[52:55]
	ds_read_b128 v[196:199], v243
	ds_read_b128 v[200:203], v243 offset:64
	s_waitcnt lgkmcnt(7)
	v_mfma_f32_16x16x32_bf16 v[56:59], v[168:171], v[4:7], v[56:59]
	s_waitcnt lgkmcnt(6)
	v_mfma_f32_16x16x32_bf16 v[56:59], v[172:175], v[8:11], v[56:59]
	ds_read_b128 v[204:207], v243 offset:2304
	ds_read_b128 v[208:211], v243 offset:2368
	s_waitcnt lgkmcnt(7)
	v_mfma_f32_16x16x32_bf16 v[44:47], v[176:179], v[4:7], v[44:47]
	s_waitcnt lgkmcnt(6)
	v_mfma_f32_16x16x32_bf16 v[44:47], v[180:183], v[8:11], v[44:47]
	ds_read_b128 v[212:215], v243 offset:4608
	ds_read_b128 v[216:219], v243 offset:4672
	s_waitcnt lgkmcnt(7)
	v_mfma_f32_16x16x32_bf16 v[48:51], v[184:187], v[4:7], v[48:51]
	s_waitcnt lgkmcnt(6)
	v_mfma_f32_16x16x32_bf16 v[48:51], v[188:191], v[8:11], v[48:51]
	ds_read_b128 v[220:223], v243 offset:6912
	ds_read_b128 v[224:227], v243 offset:6976
	s_cbranch_vccnz .LBB0_749
	v_exp_f32_e32 v78, v52
	v_exp_f32_e32 v79, v56
	v_exp_f32_e32 v106, v53
	v_exp_f32_e32 v107, v57
	v_mul_f32_e32 v109, v74, v78
	v_mul_f32_e32 v110, v74, v79
	v_exp_f32_e32 v78, v54
	v_exp_f32_e32 v84, v58
	v_exp_f32_e32 v79, v55
	v_exp_f32_e32 v85, v59
	v_mul_f32_e32 v111, v74, v106
	v_mul_f32_e32 v121, v74, v107
	v_pk_mul_f32 v[78:79], v[74:75], v[78:79]
	v_pk_mul_f32 v[84:85], v[74:75], v[84:85]
	s_mov_b64 s[6:7], 0

.LBB0_759:
	s_or_b64 exec, exec, s[4:5]
	v_cvt_pk_bf16_f32 v48, v52, v53
	v_cvt_pk_bf16_f32 v50, v54, v55
	v_cvt_pk_bf16_f32 v44, v109, v111
	v_cvt_pk_bf16_f32 v45, v78, v79
	v_cvt_pk_bf16_f32 v46, v110, v121
	v_cvt_pk_bf16_f32 v47, v84, v85
	v_cvt_pk_bf16_f32 v49, v56, v57
	v_cvt_pk_bf16_f32 v51, v58, v59
	s_waitcnt lgkmcnt(0)
	s_waitcnt lgkmcnt(0)
	v_mfma_f32_16x16x32_bf16 v[12:15], v[196:199], v[44:47], v[12:15]
	v_add_u32_e32 v56, 0x800, v102
	s_add_i32 s2, s15, -2
	s_cmp_lt_u32 s2, s12
	s_cselect_b64 s[4:5], -1, 0
	s_cmp_ge_u32 s2, s12
	s_waitcnt lgkmcnt(0)
	v_mfma_f32_16x16x32_bf16 v[12:15], v[200:203], v[48:51], v[12:15]
	s_waitcnt lgkmcnt(0)
	v_mfma_f32_16x16x32_bf16 v[24:27], v[204:207], v[44:47], v[24:27]
	v_add_u32_e32 v56, 0x1000, v102
	s_waitcnt lgkmcnt(0)
	v_mfma_f32_16x16x32_bf16 v[24:27], v[208:211], v[48:51], v[24:27]
	s_waitcnt lgkmcnt(0)
	v_mfma_f32_16x16x32_bf16 v[20:23], v[212:215], v[44:47], v[20:23]
	v_add_u32_e32 v56, 0x1800, v102
	s_waitcnt lgkmcnt(0)
	v_mfma_f32_16x16x32_bf16 v[20:23], v[216:219], v[48:51], v[20:23]
	s_waitcnt lgkmcnt(0)
	v_mfma_f32_16x16x32_bf16 v[16:19], v[220:223], v[44:47], v[16:19]
	s_waitcnt lgkmcnt(0)
	v_mfma_f32_16x16x32_bf16 v[16:19], v[224:227], v[48:51], v[16:19]
	s_cbranch_scc1 .LBB0_761
	s_and_b64 vcc, exec, s[0:1]
	s_cbranch_vccz .Lp2_e_old
	s_waitcnt vmcnt(3)
	ds_write_b128 v113, v[36:39]
	s_waitcnt vmcnt(2)
	ds_write2_b64 v242, v[40:41], v[42:43] offset1:2
	s_branch .LBB0_761
.Lp2_e_old:
	s_waitcnt vmcnt(1)
	ds_write_b128 v113, v[36:39]
	s_waitcnt vmcnt(0)
	ds_write2_b64 v242, v[40:41], v[42:43] offset1:2
.LBB0_761:
	s_andn2_b64 vcc, exec, s[4:5]
	s_waitcnt lgkmcnt(0)
	s_barrier
	s_cbranch_vccnz .LBB0_774
	s_cmp_ge_u32 s15, s12
	s_cbranch_scc1 .LBB0_764
	s_add_i32 s88, s17, 0xc0
	v_lshl_add_u64 v[40:41], s[88:89], 1, v[72:73]
	global_load_dwordx4 v[36:39], v[76:77], off offset:-8
	s_nop 0
	global_load_dwordx4 v[40:43], v[40:41], off

.LBB0_766:
	ds_read_b128 v[160:163], v119
	ds_read_b128 v[164:167], v119 offset:64
	ds_read_b128 v[168:171], v119 offset:2304
	ds_read_b128 v[172:175], v119 offset:2368
	ds_read_b128 v[176:179], v119 offset:4608
	ds_read_b128 v[180:183], v119 offset:4672
	ds_read_b128 v[184:187], v119 offset:6912
	ds_read_b128 v[188:191], v119 offset:6976
	v_cndmask_b32_e64 v78, 0, 1, s[4:5]
	s_mov_b64 s[6:7], -1
	v_cmp_ne_u32_e64 s[10:11], 1, v78
	s_andn2_b64 vcc, exec, s[4:5]
	s_waitcnt lgkmcnt(7)
	v_mfma_f32_16x16x32_bf16 v[52:55], v[160:163], v[4:7], v[52:55]
	s_waitcnt lgkmcnt(6)
	v_mfma_f32_16x16x32_bf16 v[52:55], v[164:167], v[8:11], v[52:55]
	ds_read_b128 v[196:199], v244
	ds_read_b128 v[200:203], v244 offset:64
	s_waitcnt lgkmcnt(7)
	v_mfma_f32_16x16x32_bf16 v[56:59], v[168:171], v[4:7], v[56:59]
	s_waitcnt lgkmcnt(6)
	v_mfma_f32_16x16x32_bf16 v[56:59], v[172:175], v[8:11], v[56:59]
	ds_read_b128 v[204:207], v244 offset:2304
	ds_read_b128 v[208:211], v244 offset:2368
	s_waitcnt lgkmcnt(7)
	v_mfma_f32_16x16x32_bf16 v[44:47], v[176:179], v[4:7], v[44:47]
	s_waitcnt lgkmcnt(6)
	v_mfma_f32_16x16x32_bf16 v[44:47], v[180:183], v[8:11], v[44:47]
	ds_read_b128 v[212:215], v244 offset:4608
	ds_read_b128 v[216:219], v244 offset:4672
	s_waitcnt lgkmcnt(7)
	v_mfma_f32_16x16x32_bf16 v[48:51], v[184:187], v[4:7], v[48:51]
	s_waitcnt lgkmcnt(6)
	v_mfma_f32_16x16x32_bf16 v[48:51], v[188:191], v[8:11], v[48:51]
	ds_read_b128 v[220:223], v244 offset:6912
	ds_read_b128 v[224:227], v244 offset:6976
	s_cbranch_vccnz .LBB0_768
	v_exp_f32_e32 v78, v52
	v_exp_f32_e32 v79, v56
	v_exp_f32_e32 v111, v53
	v_exp_f32_e32 v121, v57
	v_mul_f32_e32 v109, v74, v78
	v_mul_f32_e32 v110, v74, v79
	v_exp_f32_e32 v78, v54
	v_exp_f32_e32 v84, v58
	v_exp_f32_e32 v79, v55
	v_exp_f32_e32 v85, v59
	v_mul_f32_e32 v111, v74, v111
	v_mul_f32_e32 v121, v74, v121
	v_pk_mul_f32 v[78:79], v[74:75], v[78:79]
	v_pk_mul_f32 v[84:85], v[74:75], v[84:85]
	s_mov_b64 s[6:7], 0

.LBB0_779:
	s_or_b64 exec, exec, s[4:5]
	v_cvt_pk_bf16_f32 v48, v52, v53
	v_cvt_pk_bf16_f32 v50, v54, v55
	v_cvt_pk_bf16_f32 v44, v109, v111
	v_cvt_pk_bf16_f32 v45, v78, v79
	v_cvt_pk_bf16_f32 v46, v110, v121
	v_cvt_pk_bf16_f32 v47, v84, v85
	v_cvt_pk_bf16_f32 v49, v56, v57
	v_cvt_pk_bf16_f32 v51, v58, v59
	s_waitcnt lgkmcnt(0)
	s_waitcnt lgkmcnt(0)
	v_mfma_f32_16x16x32_bf16 v[12:15], v[196:199], v[44:47], v[12:15]
	v_add_u32_e32 v56, 0x800, v105
	s_andn2_b64 vcc, exec, s[0:1]
	s_waitcnt lgkmcnt(0)
	v_mfma_f32_16x16x32_bf16 v[12:15], v[200:203], v[48:51], v[12:15]
	s_waitcnt lgkmcnt(0)
	v_mfma_f32_16x16x32_bf16 v[24:27], v[204:207], v[44:47], v[24:27]
	v_add_u32_e32 v56, 0x1000, v105
	s_waitcnt lgkmcnt(0)
	v_mfma_f32_16x16x32_bf16 v[24:27], v[208:211], v[48:51], v[24:27]
	s_waitcnt lgkmcnt(0)
	v_mfma_f32_16x16x32_bf16 v[20:23], v[212:215], v[44:47], v[20:23]
	v_add_u32_e32 v56, 0x1800, v105
	s_waitcnt lgkmcnt(0)
	v_mfma_f32_16x16x32_bf16 v[20:23], v[216:219], v[48:51], v[20:23]
	s_waitcnt lgkmcnt(0)
	v_mfma_f32_16x16x32_bf16 v[16:19], v[220:223], v[44:47], v[16:19]
	s_waitcnt lgkmcnt(0)
	v_mfma_f32_16x16x32_bf16 v[16:19], v[224:227], v[48:51], v[16:19]
	s_cbranch_vccnz .LBB0_742
	s_cmp_lt_u32 s15, s12
	s_cbranch_scc0 .Lp2_o_old
	s_waitcnt vmcnt(3)
	ds_write_b128 v112, v[28:31]
	s_waitcnt vmcnt(2)
	ds_write2_b64 v238, v[32:33], v[34:35] offset1:2
	s_branch .LBB0_742
.Lp2_o_old:
	s_waitcnt vmcnt(1)
	ds_write_b128 v112, v[28:31]
	s_waitcnt vmcnt(0)
	ds_write2_b64 v238, v[32:33], v[34:35] offset1:2
	s_branch .LBB0_742

.LBB0_1003:
	s_add_i32 s0, s11, -1
	v_mad_u64_u32 v[52:53], s[0:1], s0, v250, v[52:53]
	s_lshl_b32 s0, s10, 7
	s_mov_b32 s1, s89
	v_lshl_add_u64 v[56:57], v[104:105], 0, s[0:1]
	global_load_dwordx4 v[52:55], v[52:53], off
	s_nop 0
	global_load_dwordx4 v[56:59], v[56:57], off offset:-256
	v_cndmask_b32_e64 v60, 0, 1, s[4:5]
	v_cmp_ne_u32_e64 s[0:1], 1, v60
	s_andn2_b64 vcc, exec, s[4:5]
	s_cbranch_vccnz .LBB0_1005
	s_waitcnt vmcnt(3)
	ds_write_b128 v112, v[44:47]
	s_waitcnt vmcnt(2)
	ds_write2_b64 v238, v[48:49], v[50:51] offset1:2
	s_branch .LBB0_1005

.LBB0_1015:
	s_and_b64 vcc, exec, s[8:9]
	s_cbranch_vccz .Lwin_e_old
	s_waitcnt vmcnt(3)
	ds_write_b128 v113, v[52:55]
	s_waitcnt vmcnt(2)
	ds_write2_b64 v242, v[56:57], v[58:59] offset1:2
	s_branch .LBB0_1016

.LBB0_1016:
	s_andn2_b64 vcc, exec, s[4:5]
	s_waitcnt lgkmcnt(0)
	s_barrier
	s_cbranch_vccnz .LBB0_1028
	s_cmp_gt_i32 s17, s12
	s_cbranch_scc1 .LBB0_1019
	s_ashr_i32 s1, s0, 31
	v_lshl_add_u64 v[56:57], s[0:1], 1, v[104:105]
	global_load_dwordx4 v[52:55], v[110:111], off
	s_nop 0
	global_load_dwordx4 v[56:59], v[56:57], off

.LBB0_1024:
	s_and_b64 vcc, exec, s[4:5]
	s_cbranch_vccz .LBB0_1014
	ds_read_b128 v[160:163], v118
	ds_read_b128 v[164:167], v118 offset:64
	ds_read_b128 v[168:171], v118 offset:2304
	ds_read_b128 v[172:175], v118 offset:2368
	ds_read_b128 v[176:179], v118 offset:4608
	ds_read_b128 v[180:183], v118 offset:4672
	ds_read_b128 v[184:187], v118 offset:6912
	ds_read_b128 v[188:191], v118 offset:6976
	v_add_u32_e32 v0, s43, v120
	v_cvt_f32_i32_e32 v2, v0
	s_mov_b32 s4, 2.0
	s_mov_b32 s5, 0x40400000
	v_mul_f32_e64 v0, -v96, v2
	v_mov_b32_e32 v76, v0
	v_fma_f32 v77, -v96, v2, v96
	v_fmac_f32_e32 v76, 0, v96
	v_pk_fma_f32 v[78:79], v[96:97], s[4:5], v[0:1] op_sel_hi:[1,1,0]
	s_mov_b32 s4, 0x41800000
	s_mov_b32 s5, 0x41880000
	s_waitcnt lgkmcnt(7)
	v_mfma_f32_16x16x32_bf16 v[76:79], v[160:163], v[4:7], v[76:79]
	v_pk_fma_f32 v[82:83], v[108:109], s[90:91], v[0:1] op_sel_hi:[1,1,0]
	v_pk_fma_f32 v[80:81], v[106:107], s[4:5], v[0:1] op_sel_hi:[1,1,0]
	v_pk_fma_f32 v[130:131], v[108:109], s[92:93], v[0:1] op_sel_hi:[1,1,0]
	s_waitcnt lgkmcnt(6)
	v_mfma_f32_16x16x32_bf16 v[88:91], v[164:167], v[8:11], v[76:79]
	ds_read_b128 v[196:199], v243
	ds_read_b128 v[200:203], v243 offset:64
	s_nop 2
	v_pk_fma_f32 v[128:129], v[106:107], s[34:35], v[0:1] op_sel_hi:[1,1,0]
	v_pk_fma_f32 v[134:135], v[108:109], s[22:23], v[0:1] op_sel_hi:[1,1,0]
	s_waitcnt lgkmcnt(7)
	v_mfma_f32_16x16x32_bf16 v[76:79], v[168:171], v[4:7], v[80:83]
	s_nop 2
	v_pk_fma_f32 v[132:133], v[106:107], s[72:73], v[0:1] op_sel_hi:[1,1,0]
	v_max3_f32 v0, v88, s36, v89
	s_waitcnt lgkmcnt(6)
	v_mfma_f32_16x16x32_bf16 v[84:87], v[172:175], v[8:11], v[76:79]
	ds_read_b128 v[204:207], v243 offset:2304
	ds_read_b128 v[208:211], v243 offset:2368
	s_nop 2
	v_max3_f32 v0, v0, v90, v91
	s_waitcnt lgkmcnt(7)
	v_mfma_f32_16x16x32_bf16 v[76:79], v[176:179], v[4:7], v[128:131]
	s_nop 2
	v_max3_f32 v0, v0, v84, v85
	v_max3_f32 v0, v0, v86, v87
	s_waitcnt lgkmcnt(6)
	v_mfma_f32_16x16x32_bf16 v[76:79], v[180:183], v[8:11], v[76:79]
	ds_read_b128 v[212:215], v243 offset:4608
	ds_read_b128 v[216:219], v243 offset:4672
	s_waitcnt lgkmcnt(7)
	v_mfma_f32_16x16x32_bf16 v[80:83], v[184:187], v[4:7], v[132:135]
	s_nop 4
	v_max3_f32 v0, v0, v76, v77
	v_max3_f32 v0, v0, v78, v79
	s_waitcnt lgkmcnt(6)
	v_mfma_f32_16x16x32_bf16 v[80:83], v[188:191], v[8:11], v[80:83]
	ds_read_b128 v[220:223], v243 offset:6912
	ds_read_b128 v[224:227], v243 offset:6976
	s_nop 7
	v_max3_f32 v0, v0, v80, v81
	v_max3_f32 v0, v0, v82, v83
	v_cmp_gt_f32_e32 vcc, v0, v126
	s_cbranch_vccz .LBB0_1027
	ds_bpermute_b32 v2, v115, v0
	v_max_f32_e32 v0, v0, v0
	s_waitcnt lgkmcnt(0)
	v_max_f32_e32 v2, v2, v2
	v_max_f32_e32 v0, v0, v2
	ds_bpermute_b32 v2, v114, v0
	s_waitcnt lgkmcnt(0)
	v_max3_f32 v2, v126, v0, v2
	v_sub_f32_e32 v0, v126, v2
	v_exp_f32_e32 v0, v0
	v_mov_b32_e32 v126, v2
	v_mul_f32_e32 v127, v127, v0
	v_pk_mul_f32 v[62:63], v[62:63], v[0:1] op_sel_hi:[1,0]
	v_pk_mul_f32 v[60:61], v[60:61], v[0:1] op_sel_hi:[1,0]
	v_pk_mul_f32 v[66:67], v[66:67], v[0:1] op_sel_hi:[1,0]
	v_pk_mul_f32 v[64:65], v[64:65], v[0:1] op_sel_hi:[1,0]
	v_pk_mul_f32 v[70:71], v[70:71], v[0:1] op_sel_hi:[1,0]
	v_pk_mul_f32 v[68:69], v[68:69], v[0:1] op_sel_hi:[1,0]
	v_pk_mul_f32 v[74:75], v[74:75], v[0:1] op_sel_hi:[1,0]
	v_pk_mul_f32 v[72:73], v[72:73], v[0:1] op_sel_hi:[1,0]
.LBB0_1027:
	v_sub_f32_e32 v0, v88, v126
	v_exp_f32_e32 v0, v0
	v_sub_f32_e32 v3, v89, v126
	v_exp_f32_e32 v3, v3
	v_sub_f32_e32 v88, v90, v126
	v_exp_f32_e32 v88, v88
	v_sub_f32_e32 v89, v91, v126
	v_exp_f32_e32 v89, v89
	v_sub_f32_e32 v84, v84, v126
	v_add_f32_e32 v2, 0, v0
	v_exp_f32_e32 v84, v84
	v_sub_f32_e32 v85, v85, v126
	v_add_f32_e32 v2, v3, v2
	v_exp_f32_e32 v85, v85
	v_sub_f32_e32 v86, v86, v126
	v_add_f32_e32 v2, v88, v2
	v_exp_f32_e32 v86, v86
	v_sub_f32_e32 v87, v87, v126
	v_add_f32_e32 v2, v89, v2
	v_exp_f32_e32 v87, v87
	v_cvt_pk_bf16_f32 v128, v0, v3
	v_sub_f32_e32 v0, v76, v126
	v_add_f32_e32 v2, v84, v2
	v_exp_f32_e32 v0, v0
	v_sub_f32_e32 v3, v77, v126
	v_add_f32_e32 v2, v85, v2
	v_exp_f32_e32 v3, v3
	v_sub_f32_e32 v76, v78, v126
	v_add_f32_e32 v2, v86, v2
	v_exp_f32_e32 v76, v76
	v_sub_f32_e32 v77, v79, v126
	v_add_f32_e32 v2, v87, v2
	v_exp_f32_e32 v77, v77
	v_sub_f32_e32 v78, v80, v126
	v_add_f32_e32 v2, v0, v2
	v_exp_f32_e32 v78, v78
	v_sub_f32_e32 v79, v81, v126
	v_add_f32_e32 v2, v3, v2
	v_exp_f32_e32 v79, v79
	v_add_f32_e32 v2, v76, v2
	v_add_f32_e32 v2, v77, v2
	v_add_f32_e32 v2, v78, v2
	v_cvt_pk_bf16_f32 v129, v88, v89
	v_add_f32_e32 v2, v79, v2
	v_cvt_pk_bf16_f32 v89, v76, v77
	v_cvt_pk_bf16_f32 v90, v78, v79
	v_cvt_pk_bf16_f32 v130, v84, v85
	v_cvt_pk_bf16_f32 v131, v86, v87
	v_sub_f32_e32 v80, v82, v126
	v_sub_f32_e32 v81, v83, v126
	s_waitcnt lgkmcnt(0)
	s_waitcnt lgkmcnt(0)
	v_mfma_f32_16x16x32_bf16 v[60:63], v[196:199], v[128:131], v[60:63]
	v_exp_f32_e32 v80, v80
	v_exp_f32_e32 v81, v81
	v_cvt_pk_bf16_f32 v88, v0, v3
	v_add_u32_e32 v0, 0x800, v123
	v_add_f32_e32 v2, v80, v2
	v_cvt_pk_bf16_f32 v91, v80, v81
	v_add_f32_e32 v2, v81, v2
	v_add_f32_e32 v2, v127, v2
	s_waitcnt lgkmcnt(0)
	v_mfma_f32_16x16x32_bf16 v[76:79], v[200:203], v[88:91], v[60:63]
	s_nop 2
	s_waitcnt lgkmcnt(0)
	v_mfma_f32_16x16x32_bf16 v[60:63], v[204:207], v[128:131], v[64:67]
	s_nop 2
	v_add_u32_e32 v0, 0x1000, v123
	s_waitcnt lgkmcnt(0)
	v_mfma_f32_16x16x32_bf16 v[80:83], v[208:211], v[88:91], v[60:63]
	s_nop 2
	v_add_u32_e32 v0, 0x1800, v123
	s_waitcnt lgkmcnt(1)
	v_mfma_f32_16x16x32_bf16 v[60:63], v[212:215], v[128:131], v[68:71]
	s_waitcnt lgkmcnt(0)
	v_mfma_f32_16x16x32_bf16 v[84:87], v[216:219], v[88:91], v[60:63]
	s_nop 4
	s_waitcnt lgkmcnt(0)
	v_mfma_f32_16x16x32_bf16 v[60:63], v[220:223], v[128:131], v[72:75]
	v_mov_b32_e32 v0, v126
	v_mfma_f32_16x16x32_bf16 v[88:91], v[224:227], v[88:91], v[60:63]
	s_cmp_lt_i32 s17, s11
	s_cselect_b64 s[4:5], -1, 0
	s_cmp_ge_i32 s17, s11
	s_cbranch_scc0 .LBB0_1015
	s_branch .LBB0_1016

.LBB0_1029:
	s_and_b64 vcc, exec, s[4:5]
	s_cbranch_vccz .LBB0_1023
	ds_read_b128 v[160:163], v119
	ds_read_b128 v[164:167], v119 offset:64
	ds_read_b128 v[168:171], v119 offset:2304
	ds_read_b128 v[172:175], v119 offset:2368
	ds_read_b128 v[176:179], v119 offset:4608
	ds_read_b128 v[180:183], v119 offset:4672
	ds_read_b128 v[184:187], v119 offset:6912
	ds_read_b128 v[188:191], v119 offset:6976
	v_or_b32_e32 v3, s1, v98
	v_sub_u32_e32 v3, v103, v3
	v_cvt_f32_i32_e32 v3, v3
	s_mov_b32 s4, 2.0
	s_mov_b32 s5, 0x40400000
	v_mul_f32_e64 v68, -v96, v3
	v_pk_fma_f32 v[62:63], v[96:97], s[4:5], v[68:69] op_sel_hi:[1,1,0]
	s_mov_b32 s4, 0x41800000
	s_mov_b32 s5, 0x41880000
	v_mov_b32_e32 v60, v68
	v_pk_fma_f32 v[66:67], v[108:109], s[90:91], v[68:69] op_sel_hi:[1,1,0]
	v_pk_fma_f32 v[64:65], v[106:107], s[4:5], v[68:69] op_sel_hi:[1,1,0]
	v_pk_fma_f32 v[128:129], v[108:109], s[92:93], v[68:69] op_sel_hi:[1,1,0]
	v_pk_fma_f32 v[126:127], v[106:107], s[34:35], v[68:69] op_sel_hi:[1,1,0]
	v_pk_fma_f32 v[132:133], v[108:109], s[22:23], v[68:69] op_sel_hi:[1,1,0]
	v_pk_fma_f32 v[130:131], v[106:107], s[72:73], v[68:69] op_sel_hi:[1,1,0]
	v_fma_f32 v61, -v96, v3, v96
	v_fmac_f32_e32 v60, 0, v96
	s_nop 0
	s_waitcnt lgkmcnt(7)
	v_mfma_f32_16x16x32_bf16 v[60:63], v[160:163], v[4:7], v[60:63]
	s_waitcnt lgkmcnt(6)
	v_mfma_f32_16x16x32_bf16 v[72:75], v[164:167], v[8:11], v[60:63]
	ds_read_b128 v[196:199], v244
	ds_read_b128 v[200:203], v244 offset:64
	s_nop 4
	s_nop 1
	v_max3_f32 v3, v72, s36, v73
	s_waitcnt lgkmcnt(7)
	v_mfma_f32_16x16x32_bf16 v[60:63], v[168:171], v[4:7], v[64:67]
	s_nop 2
	v_max3_f32 v3, v3, v74, v75
	s_waitcnt lgkmcnt(6)
	v_mfma_f32_16x16x32_bf16 v[68:71], v[172:175], v[8:11], v[60:63]
	ds_read_b128 v[204:207], v244 offset:2304
	ds_read_b128 v[208:211], v244 offset:2368
	s_nop 2
	s_nop 2
	v_max3_f32 v3, v3, v68, v69
	s_waitcnt lgkmcnt(7)
	v_mfma_f32_16x16x32_bf16 v[60:63], v[176:179], v[4:7], v[126:129]
	s_nop 2
	v_max3_f32 v3, v3, v70, v71
	s_waitcnt lgkmcnt(6)
	v_mfma_f32_16x16x32_bf16 v[60:63], v[180:183], v[8:11], v[60:63]
	ds_read_b128 v[212:215], v244 offset:4608
	ds_read_b128 v[216:219], v244 offset:4672
	s_waitcnt lgkmcnt(7)
	v_mfma_f32_16x16x32_bf16 v[64:67], v[184:187], v[4:7], v[130:133]
	s_nop 4
	v_max3_f32 v3, v3, v60, v61
	v_max3_f32 v3, v3, v62, v63
	s_waitcnt lgkmcnt(6)
	v_mfma_f32_16x16x32_bf16 v[64:67], v[188:191], v[8:11], v[64:67]
	ds_read_b128 v[220:223], v244 offset:6912
	ds_read_b128 v[224:227], v244 offset:6976
	s_nop 7
	v_max3_f32 v3, v3, v64, v65
	v_max3_f32 v3, v3, v66, v67
	v_cmp_gt_f32_e32 vcc, v3, v0
	s_cbranch_vccz .LBB0_1032
	ds_bpermute_b32 v126, v115, v3
	v_max_f32_e32 v3, v3, v3
	s_waitcnt lgkmcnt(0)
	v_max_f32_e32 v126, v126, v126
	v_max_f32_e32 v3, v3, v126
	ds_bpermute_b32 v126, v114, v3
	s_waitcnt lgkmcnt(0)
	v_max3_f32 v3, v0, v3, v126
	v_sub_f32_e32 v0, v0, v3
	v_exp_f32_e32 v0, v0
	s_nop 0
	v_mul_f32_e32 v2, v2, v0
	v_pk_mul_f32 v[78:79], v[78:79], v[0:1] op_sel_hi:[1,0]
	v_pk_mul_f32 v[76:77], v[76:77], v[0:1] op_sel_hi:[1,0]
	v_pk_mul_f32 v[82:83], v[82:83], v[0:1] op_sel_hi:[1,0]
	v_pk_mul_f32 v[80:81], v[80:81], v[0:1] op_sel_hi:[1,0]
	v_pk_mul_f32 v[86:87], v[86:87], v[0:1] op_sel_hi:[1,0]
	v_pk_mul_f32 v[84:85], v[84:85], v[0:1] op_sel_hi:[1,0]
	v_pk_mul_f32 v[90:91], v[90:91], v[0:1] op_sel_hi:[1,0]
	v_pk_mul_f32 v[88:89], v[88:89], v[0:1] op_sel_hi:[1,0]
	v_mov_b32_e32 v0, v3
.LBB0_1032:
	v_sub_f32_e32 v3, v72, v0
	v_exp_f32_e32 v3, v3
	v_sub_f32_e32 v73, v73, v0
	v_exp_f32_e32 v73, v73
	v_sub_f32_e32 v74, v74, v0
	v_exp_f32_e32 v74, v74
	v_sub_f32_e32 v75, v75, v0
	v_exp_f32_e32 v75, v75
	v_sub_f32_e32 v68, v68, v0
	v_add_f32_e32 v72, 0, v3
	v_exp_f32_e32 v68, v68
	v_sub_f32_e32 v69, v69, v0
	v_add_f32_e32 v72, v73, v72
	v_exp_f32_e32 v69, v69
	v_sub_f32_e32 v70, v70, v0
	v_add_f32_e32 v72, v74, v72
	v_exp_f32_e32 v70, v70
	v_sub_f32_e32 v71, v71, v0
	v_add_f32_e32 v72, v75, v72
	v_exp_f32_e32 v71, v71
	v_cvt_pk_bf16_f32 v128, v3, v73
	v_sub_f32_e32 v3, v60, v0
	v_add_f32_e32 v72, v68, v72
	v_exp_f32_e32 v3, v3
	v_sub_f32_e32 v61, v61, v0
	v_add_f32_e32 v72, v69, v72
	v_exp_f32_e32 v61, v61
	v_sub_f32_e32 v62, v62, v0
	v_add_f32_e32 v72, v70, v72
	v_exp_f32_e32 v62, v62
	v_sub_f32_e32 v63, v63, v0
	v_add_f32_e32 v72, v71, v72
	v_exp_f32_e32 v63, v63
	v_sub_f32_e32 v64, v64, v0
	v_add_f32_e32 v60, v3, v72
	v_exp_f32_e32 v64, v64
	v_sub_f32_e32 v65, v65, v0
	v_add_f32_e32 v60, v61, v60
	v_exp_f32_e32 v65, v65
	v_sub_f32_e32 v66, v66, v0
	v_add_f32_e32 v60, v62, v60
	v_exp_f32_e32 v66, v66
	v_sub_f32_e32 v67, v67, v0
	v_add_f32_e32 v60, v63, v60
	v_exp_f32_e32 v67, v67
	v_add_f32_e32 v60, v64, v60
	v_add_f32_e32 v60, v65, v60
	v_add_f32_e32 v60, v66, v60
	v_add_f32_e32 v60, v67, v60
	v_cvt_pk_bf16_f32 v72, v3, v61
	v_cvt_pk_bf16_f32 v73, v62, v63
	v_add_f32_e32 v127, v2, v60
	v_cvt_pk_bf16_f32 v129, v74, v75
	v_cvt_pk_bf16_f32 v74, v64, v65
	v_cvt_pk_bf16_f32 v75, v66, v67
	v_cvt_pk_bf16_f32 v130, v68, v69
	v_cvt_pk_bf16_f32 v131, v70, v71
	v_add_u32_e32 v2, 0x800, v124
	s_waitcnt lgkmcnt(2)
	s_waitcnt lgkmcnt(0)
	v_mfma_f32_16x16x32_bf16 v[60:63], v[196:199], v[128:131], v[76:79]
	v_mov_b32_e32 v126, v0
	s_waitcnt lgkmcnt(1)
	v_mfma_f32_16x16x32_bf16 v[60:63], v[200:203], v[72:75], v[60:63]
	v_add_u32_e32 v2, 0x1000, v124
	s_waitcnt lgkmcnt(1)
	v_mfma_f32_16x16x32_bf16 v[64:67], v[204:207], v[128:131], v[80:83]
	v_mfma_f32_16x16x32_bf16 v[64:67], v[208:211], v[72:75], v[64:67]
	v_add_u32_e32 v2, 0x1800, v124
	s_waitcnt lgkmcnt(1)
	v_mfma_f32_16x16x32_bf16 v[68:71], v[212:215], v[128:131], v[84:87]
	v_mfma_f32_16x16x32_bf16 v[68:71], v[216:219], v[72:75], v[68:71]
	s_waitcnt lgkmcnt(0)
	v_mfma_f32_16x16x32_bf16 v[76:79], v[220:223], v[128:131], v[88:91]
	v_mfma_f32_16x16x32_bf16 v[72:75], v[224:227], v[72:75], v[76:79]
	s_andn2_b64 vcc, exec, s[8:9]
	s_cbranch_vccnz .LBB0_1007
.LBB0_1033:
	s_cmp_gt_i32 s17, s12
	s_cbranch_scc1 .Lwin_o_old
	s_waitcnt vmcnt(3)
	ds_write_b128 v112, v[44:47]
	s_waitcnt vmcnt(2)
	ds_write2_b64 v238, v[48:49], v[50:51] offset1:2
	s_branch .LBB0_1007
